# GEMM K-loops (6 instances): coalesced 8 paired lgkmcnt waits per iteration before independent MFMA pairs (on top of v49)
# baseline (speedup 1.0000x reference)
; #define PIN() do { asm volatile("" ::: "memory"); __builtin_amdgcn_sched_barrier(0); } while (0)
;     ...
;     for (int kt = kt0; kt < kt1; ++kt) {
;       const char* cur = smem + ((kt - kt0) & 1) * GBUF;
;       if (WM == 1) { GLOADG(kt + 1 < kt1 ? kt + 1 : kt); PIN(); }
;       const char* ab = cur + (wm * 32 * WM + l31) * GSTR + hh * 16;
;       const char* wb = cur + (256 + wn * 128 + l31) * GSTR + hh * 16;
;       bf16x8 tfA, tfA1, tfB, tfB1, wfA0, wfA1, wfA2, wfA3, wfB0, wfB1, wfB2, wfB3;
;     ...
;       if (WM == 1) {
;         LDFR(tfA, tfA1, wfA0, wfA1, wfA2, wfA3, 0);
;         LDFR(tfB, tfB1, wfB0, wfB1, wfB2, wfB3, 1);
;         PIN();
;         DOMM(tfA, tfA1, wfA0, wfA1, wfA2, wfA3);
;         PIN();
;         LDFR(tfA, tfA1, wfA0, wfA1, wfA2, wfA3, 2);
;         PIN();
;         DOMM(tfB, tfB1, wfB0, wfB1, wfB2, wfB3);
;         PIN();
;         LDFR(tfB, tfB1, wfB0, wfB1, wfB2, wfB3, 3);
;         PIN();
;         DOMM(tfA, tfA1, wfA0, wfA1, wfA2, wfA3);
;         DOMM(tfB, tfB1, wfB0, wfB1, wfB2, wfB3);
;       } else {
;         char* nb_ = smem + ((kt + 1 - kt0) & 1) * GBUF + lo;
;     ...
;         LDFR(tfA, tfA1, wfA0, wfA1, wfA2, wfA3, 0);
;         PIN();
;         DOMM(tfA, tfA1, wfA0, wfA1, wfA2, wfA3);
;         PIN();
;         LDFR(tfA, tfA1, wfA0, wfA1, wfA2, wfA3, 1);
;         PIN();
;         DOMM(tfA, tfA1, wfA0, wfA1, wfA2, wfA3);
;         PIN();
;         LDFR(tfA, tfA1, wfA0, wfA1, wfA2, wfA3, 2);
;         PIN();
;         MM2(0, tfA, wfA0, wfA1, 0, 1); PIN(); *(uint4*)(nb_) = ra0; PIN();
;         MM2(0, tfA, wfA2, wfA3, 2, 3); PIN(); *(uint4*)(nb_ + 64 * GSTR) = ra1; PIN();
;         MM2(1, tfA1, wfA0, wfA1, 0, 1); PIN(); *(uint4*)(nb_ + 128 * GSTR) = ra2; PIN();
;         MM2(1, tfA1, wfA2, wfA3, 2, 3); PIN(); *(uint4*)(nb_ + 192 * GSTR) = ra3; PIN();
;         LDFR(tfA, tfA1, wfA0, wfA1, wfA2, wfA3, 3);
;         PIN();
;         MM2(0, tfA, wfA0, wfA1, 0, 1); PIN(); *(uint4*)(nb_ + 256 * GSTR) = rw0; PIN();
;         MM2(0, tfA, wfA2, wfA3, 2, 3); PIN(); *(uint4*)(nb_ + 320 * GSTR) = rw1; PIN();
;         MM2(1, tfA1, wfA0, wfA1, 0, 1); PIN(); *(uint4*)(nb_ + 384 * GSTR) = rw2; PIN();
;         MM2(1, tfA1, wfA2, wfA3, 2, 3); PIN(); *(uint4*)(nb_ + 448 * GSTR) = rw3; PIN();
;         GLOADG(kt + 2 < kt1 ? kt + 2 : kt);
.LBB0_24:
	s_add_i32 s24, s28, s27
	s_bitcmp1_b32 s27, 0
	s_cselect_b32 s25, 0x12000, 0
	s_add_i32 s25, s25, 0
	v_add3_u32 v140, s25, v189, v190
	v_add3_u32 v201, s25, v191, v190
	ds_read_b128 v[192:195], v140
	ds_read_b128 v[196:199], v140 offset:4608
	ds_read_b128 v[214:217], v201
	ds_read_b128 v[218:221], v201 offset:4608
	ds_read_b128 v[222:225], v201 offset:9216
	ds_read_b128 v[226:229], v201 offset:13824
	s_add_i32 s27, s27, 1
	s_bitcmp1_b32 s27, 0
	s_cselect_b32 s25, 0x12000, 0
	v_add_u32_e32 v203, s25, v188
	s_waitcnt lgkmcnt(2)
	v_mfma_f32_32x32x16_bf16 v[112:127], v[192:195], v[214:217], v[112:127]
	v_mfma_f32_32x32x16_bf16 v[96:111], v[192:195], v[218:221], v[96:111]
	s_waitcnt lgkmcnt(0)
	v_mfma_f32_32x32x16_bf16 v[80:95], v[192:195], v[222:225], v[80:95]
	v_mfma_f32_32x32x16_bf16 v[64:79], v[192:195], v[226:229], v[64:79]
	v_mfma_f32_32x32x16_bf16 v[48:63], v[196:199], v[214:217], v[48:63]
	v_mfma_f32_32x32x16_bf16 v[32:47], v[196:199], v[218:221], v[32:47]
	v_mfma_f32_32x32x16_bf16 v[16:31], v[196:199], v[222:225], v[16:31]
	v_mfma_f32_32x32x16_bf16 v[0:15], v[196:199], v[226:229], v[0:15]
	ds_read_b128 v[192:195], v140 offset:32
	ds_read_b128 v[196:199], v140 offset:4640
	ds_read_b128 v[214:217], v201 offset:32
	ds_read_b128 v[218:221], v201 offset:4640
	ds_read_b128 v[222:225], v201 offset:9248
	ds_read_b128 v[226:229], v201 offset:13856
	s_waitcnt lgkmcnt(2)
	v_mfma_f32_32x32x16_bf16 v[112:127], v[192:195], v[214:217], v[112:127]
	v_mfma_f32_32x32x16_bf16 v[96:111], v[192:195], v[218:221], v[96:111]
	s_waitcnt lgkmcnt(0)
	v_mfma_f32_32x32x16_bf16 v[80:95], v[192:195], v[222:225], v[80:95]
	v_mfma_f32_32x32x16_bf16 v[64:79], v[192:195], v[226:229], v[64:79]
	v_mfma_f32_32x32x16_bf16 v[48:63], v[196:199], v[214:217], v[48:63]
	v_mfma_f32_32x32x16_bf16 v[32:47], v[196:199], v[218:221], v[32:47]
	v_mfma_f32_32x32x16_bf16 v[16:31], v[196:199], v[222:225], v[16:31]
	v_mfma_f32_32x32x16_bf16 v[0:15], v[196:199], v[226:229], v[0:15]
	ds_read_b128 v[192:195], v140 offset:64
	ds_read_b128 v[196:199], v140 offset:4672
	ds_read_b128 v[214:217], v201 offset:64
	ds_read_b128 v[218:221], v201 offset:4672
	ds_read_b128 v[222:225], v201 offset:9280
	ds_read_b128 v[226:229], v201 offset:13888
	s_waitcnt lgkmcnt(2)
	v_mfma_f32_32x32x16_bf16 v[112:127], v[192:195], v[214:217], v[112:127]
	v_mfma_f32_32x32x16_bf16 v[96:111], v[192:195], v[218:221], v[96:111]
	s_waitcnt vmcnt(7)
	ds_write_b128 v203, v[158:161]
	s_waitcnt lgkmcnt(1)
	v_mfma_f32_32x32x16_bf16 v[80:95], v[192:195], v[222:225], v[80:95]
	v_mfma_f32_32x32x16_bf16 v[64:79], v[192:195], v[226:229], v[64:79]
	s_waitcnt vmcnt(6)
	ds_write_b128 v203, v[154:157] offset:9216
	v_mfma_f32_32x32x16_bf16 v[48:63], v[196:199], v[214:217], v[48:63]
	v_mfma_f32_32x32x16_bf16 v[32:47], v[196:199], v[218:221], v[32:47]
	s_waitcnt vmcnt(5)
	ds_write_b128 v203, v[150:153] offset:18432
	v_mfma_f32_32x32x16_bf16 v[16:31], v[196:199], v[222:225], v[16:31]
	v_mfma_f32_32x32x16_bf16 v[0:15], v[196:199], v[226:229], v[0:15]
	s_waitcnt vmcnt(4)
	ds_write_b128 v203, v[146:149] offset:27648
	ds_read_b128 v[146:149], v140 offset:96
	ds_read_b128 v[150:153], v140 offset:4704
	ds_read_b128 v[154:157], v201 offset:96
	ds_read_b128 v[158:161], v201 offset:4704
	ds_read_b128 v[192:195], v201 offset:9312
	ds_read_b128 v[196:199], v201 offset:13920
	s_waitcnt lgkmcnt(2)
	v_mfma_f32_32x32x16_bf16 v[112:127], v[146:149], v[154:157], v[112:127]
	v_mfma_f32_32x32x16_bf16 v[96:111], v[146:149], v[158:161], v[96:111]
	s_waitcnt vmcnt(3)
	ds_write_b128 v203, v[142:145] offset:36864
	s_waitcnt lgkmcnt(1)
	v_mfma_f32_32x32x16_bf16 v[80:95], v[146:149], v[192:195], v[80:95]
	v_mfma_f32_32x32x16_bf16 v[64:79], v[146:149], v[196:199], v[64:79]
	s_waitcnt vmcnt(2)
	ds_write_b128 v203, v[136:139] offset:46080
	v_mfma_f32_32x32x16_bf16 v[48:63], v[150:153], v[154:157], v[48:63]
	v_mfma_f32_32x32x16_bf16 v[32:47], v[150:153], v[158:161], v[32:47]
	s_waitcnt vmcnt(1)
	ds_write_b128 v203, v[132:135] offset:55296
	v_mfma_f32_32x32x16_bf16 v[16:31], v[150:153], v[192:195], v[16:31]
	v_mfma_f32_32x32x16_bf16 v[0:15], v[150:153], v[196:199], v[0:15]
	s_waitcnt vmcnt(0)
	ds_write_b128 v203, v[128:131] offset:64512
	s_add_i32 s25, s24, 2
	s_cmp_lt_u32 s25, s29
	s_cselect_b32 s24, s25, s24
	s_lshl_b32 s96, s24, 7
	v_lshl_add_u64 v[128:129], v[170:171], 0, s[96:97]
	v_lshl_add_u64 v[130:131], v[174:175], 0, s[96:97]
	global_load_dwordx4 v[158:161], v[128:129], off
	global_load_dwordx4 v[154:157], v[130:131], off
	v_lshl_add_u64 v[128:129], v[176:177], 0, s[96:97]
	v_lshl_add_u64 v[130:131], v[178:179], 0, s[96:97]
	global_load_dwordx4 v[150:153], v[128:129], off
	global_load_dwordx4 v[146:149], v[130:131], off
	v_lshl_add_u64 v[128:129], v[172:173], 0, s[96:97]
	v_lshl_add_u64 v[130:131], v[180:181], 0, s[96:97]
	global_load_dwordx4 v[142:145], v[128:129], off
	global_load_dwordx4 v[136:139], v[130:131], off
	v_lshl_add_u64 v[128:129], v[182:183], 0, s[96:97]
	v_lshl_add_u64 v[130:131], v[184:185], 0, s[96:97]
	global_load_dwordx4 v[132:135], v[128:129], off
	s_nop 0
	global_load_dwordx4 v[128:131], v[130:131], off
	s_add_i32 s24, s28, s27
	s_cmp_ge_u32 s24, s29
	s_waitcnt lgkmcnt(0)
	s_barrier
	s_cbranch_scc0 .LBB0_24

; #define PIN() do { asm volatile("" ::: "memory"); __builtin_amdgcn_sched_barrier(0); } while (0)
;     ...
;     for (int kt = kt0; kt < kt1; ++kt) {
;       const char* cur = smem + ((kt - kt0) & 1) * GBUF;
;       if (WM == 1) { GLOADG(kt + 1 < kt1 ? kt + 1 : kt); PIN(); }
;       const char* ab = cur + (wm * 32 * WM + l31) * GSTR + hh * 16;
;       const char* wb = cur + (256 + wn * 128 + l31) * GSTR + hh * 16;
;       bf16x8 tfA, tfA1, tfB, tfB1, wfA0, wfA1, wfA2, wfA3, wfB0, wfB1, wfB2, wfB3;
;     ...
;       if (WM == 1) {
;         LDFR(tfA, tfA1, wfA0, wfA1, wfA2, wfA3, 0);
;         LDFR(tfB, tfB1, wfB0, wfB1, wfB2, wfB3, 1);
;         PIN();
;         DOMM(tfA, tfA1, wfA0, wfA1, wfA2, wfA3);
;         PIN();
;         LDFR(tfA, tfA1, wfA0, wfA1, wfA2, wfA3, 2);
;         PIN();
;         DOMM(tfB, tfB1, wfB0, wfB1, wfB2, wfB3);
;         PIN();
;         LDFR(tfB, tfB1, wfB0, wfB1, wfB2, wfB3, 3);
;         PIN();
;         DOMM(tfA, tfA1, wfA0, wfA1, wfA2, wfA3);
;         DOMM(tfB, tfB1, wfB0, wfB1, wfB2, wfB3);
;       } else {
;         char* nb_ = smem + ((kt + 1 - kt0) & 1) * GBUF + lo;
;     ...
;         LDFR(tfA, tfA1, wfA0, wfA1, wfA2, wfA3, 0);
;         PIN();
;         DOMM(tfA, tfA1, wfA0, wfA1, wfA2, wfA3);
;         PIN();
;         LDFR(tfA, tfA1, wfA0, wfA1, wfA2, wfA3, 1);
;         PIN();
;         DOMM(tfA, tfA1, wfA0, wfA1, wfA2, wfA3);
;         PIN();
;         LDFR(tfA, tfA1, wfA0, wfA1, wfA2, wfA3, 2);
;         PIN();
;         MM2(0, tfA, wfA0, wfA1, 0, 1); PIN(); *(uint4*)(nb_) = ra0; PIN();
;         MM2(0, tfA, wfA2, wfA3, 2, 3); PIN(); *(uint4*)(nb_ + 64 * GSTR) = ra1; PIN();
;         MM2(1, tfA1, wfA0, wfA1, 0, 1); PIN(); *(uint4*)(nb_ + 128 * GSTR) = ra2; PIN();
;         MM2(1, tfA1, wfA2, wfA3, 2, 3); PIN(); *(uint4*)(nb_ + 192 * GSTR) = ra3; PIN();
;         LDFR(tfA, tfA1, wfA0, wfA1, wfA2, wfA3, 3);
;         PIN();
;         MM2(0, tfA, wfA0, wfA1, 0, 1); PIN(); *(uint4*)(nb_ + 256 * GSTR) = rw0; PIN();
;         MM2(0, tfA, wfA2, wfA3, 2, 3); PIN(); *(uint4*)(nb_ + 320 * GSTR) = rw1; PIN();
;         MM2(1, tfA1, wfA0, wfA1, 0, 1); PIN(); *(uint4*)(nb_ + 384 * GSTR) = rw2; PIN();
;         MM2(1, tfA1, wfA2, wfA3, 2, 3); PIN(); *(uint4*)(nb_ + 448 * GSTR) = rw3; PIN();
;         GLOADG(kt + 2 < kt1 ? kt + 2 : kt);
.LBB0_62:
	s_bitcmp1_b32 s0, 0
	s_cselect_b32 s1, 0x12000, 0
	s_add_i32 s1, s1, 0
	v_add3_u32 v191, s1, v187, v188
	v_add3_u32 v201, s1, v189, v188
	ds_read_b128 v[192:195], v191
	ds_read_b128 v[196:199], v191 offset:4608
	ds_read_b128 v[214:217], v201
	ds_read_b128 v[218:221], v201 offset:4608
	ds_read_b128 v[222:225], v201 offset:9216
	ds_read_b128 v[226:229], v201 offset:13824
	s_add_i32 s1, s0, 1
	s_bitcmp1_b32 s1, 0
	s_cselect_b32 s3, 0x12000, 0
	v_add_u32_e32 v203, s3, v186
	s_waitcnt lgkmcnt(2)
	v_mfma_f32_32x32x16_bf16 v[112:127], v[192:195], v[214:217], v[112:127]
	v_mfma_f32_32x32x16_bf16 v[96:111], v[192:195], v[218:221], v[96:111]
	s_waitcnt lgkmcnt(0)
	v_mfma_f32_32x32x16_bf16 v[80:95], v[192:195], v[222:225], v[80:95]
	v_mfma_f32_32x32x16_bf16 v[64:79], v[192:195], v[226:229], v[64:79]
	v_mfma_f32_32x32x16_bf16 v[48:63], v[196:199], v[214:217], v[48:63]
	v_mfma_f32_32x32x16_bf16 v[32:47], v[196:199], v[218:221], v[32:47]
	v_mfma_f32_32x32x16_bf16 v[16:31], v[196:199], v[222:225], v[16:31]
	v_mfma_f32_32x32x16_bf16 v[0:15], v[196:199], v[226:229], v[0:15]
	ds_read_b128 v[192:195], v191 offset:32
	ds_read_b128 v[196:199], v191 offset:4640
	ds_read_b128 v[214:217], v201 offset:32
	ds_read_b128 v[218:221], v201 offset:4640
	ds_read_b128 v[222:225], v201 offset:9248
	ds_read_b128 v[226:229], v201 offset:13856
	s_waitcnt lgkmcnt(2)
	v_mfma_f32_32x32x16_bf16 v[112:127], v[192:195], v[214:217], v[112:127]
	v_mfma_f32_32x32x16_bf16 v[96:111], v[192:195], v[218:221], v[96:111]
	s_waitcnt lgkmcnt(0)
	v_mfma_f32_32x32x16_bf16 v[80:95], v[192:195], v[222:225], v[80:95]
	v_mfma_f32_32x32x16_bf16 v[64:79], v[192:195], v[226:229], v[64:79]
	v_mfma_f32_32x32x16_bf16 v[48:63], v[196:199], v[214:217], v[48:63]
	v_mfma_f32_32x32x16_bf16 v[32:47], v[196:199], v[218:221], v[32:47]
	v_mfma_f32_32x32x16_bf16 v[16:31], v[196:199], v[222:225], v[16:31]
	v_mfma_f32_32x32x16_bf16 v[0:15], v[196:199], v[226:229], v[0:15]
	ds_read_b128 v[192:195], v191 offset:64
	ds_read_b128 v[196:199], v191 offset:4672
	ds_read_b128 v[214:217], v201 offset:64
	ds_read_b128 v[218:221], v201 offset:4672
	ds_read_b128 v[222:225], v201 offset:9280
	ds_read_b128 v[226:229], v201 offset:13888
	s_waitcnt lgkmcnt(2)
	v_mfma_f32_32x32x16_bf16 v[112:127], v[192:195], v[214:217], v[112:127]
	v_mfma_f32_32x32x16_bf16 v[96:111], v[192:195], v[218:221], v[96:111]
	s_waitcnt vmcnt(7)
	ds_write_b128 v203, v[150:153]
	s_waitcnt lgkmcnt(1)
	v_mfma_f32_32x32x16_bf16 v[80:95], v[192:195], v[222:225], v[80:95]
	v_mfma_f32_32x32x16_bf16 v[64:79], v[192:195], v[226:229], v[64:79]
	s_waitcnt vmcnt(6)
	ds_write_b128 v203, v[128:131] offset:9216
	v_mfma_f32_32x32x16_bf16 v[48:63], v[196:199], v[214:217], v[48:63]
	v_mfma_f32_32x32x16_bf16 v[32:47], v[196:199], v[218:221], v[32:47]
	s_waitcnt vmcnt(5)
	ds_write_b128 v203, v[136:139] offset:18432
	v_mfma_f32_32x32x16_bf16 v[16:31], v[196:199], v[222:225], v[16:31]
	v_mfma_f32_32x32x16_bf16 v[0:15], v[196:199], v[226:229], v[0:15]
	s_waitcnt vmcnt(4)
	ds_write_b128 v203, v[146:149] offset:27648
	ds_read_b128 v[128:131], v191 offset:96
	ds_read_b128 v[136:139], v191 offset:4704
	ds_read_b128 v[146:149], v201 offset:96
	ds_read_b128 v[150:153], v201 offset:4704
	ds_read_b128 v[192:195], v201 offset:9312
	ds_read_b128 v[196:199], v201 offset:13920
	s_waitcnt lgkmcnt(2)
	v_mfma_f32_32x32x16_bf16 v[112:127], v[128:131], v[146:149], v[112:127]
	v_mfma_f32_32x32x16_bf16 v[96:111], v[128:131], v[150:153], v[96:111]
	s_waitcnt vmcnt(3)
	ds_write_b128 v203, v[132:135] offset:36864
	s_waitcnt lgkmcnt(1)
	v_mfma_f32_32x32x16_bf16 v[80:95], v[128:131], v[192:195], v[80:95]
	v_mfma_f32_32x32x16_bf16 v[64:79], v[128:131], v[196:199], v[64:79]
	s_waitcnt vmcnt(2)
	ds_write_b128 v203, v[142:145] offset:46080
	v_mfma_f32_32x32x16_bf16 v[48:63], v[136:139], v[146:149], v[48:63]
	v_mfma_f32_32x32x16_bf16 v[32:47], v[136:139], v[150:153], v[32:47]
	s_waitcnt vmcnt(1)
	ds_write_b128 v203, v[158:161] offset:55296
	v_mfma_f32_32x32x16_bf16 v[16:31], v[136:139], v[192:195], v[16:31]
	v_mfma_f32_32x32x16_bf16 v[0:15], v[136:139], v[196:199], v[0:15]
	s_waitcnt vmcnt(0)
	ds_write_b128 v203, v[154:157] offset:64512
	s_add_i32 s3, s0, 2
	s_cmp_lt_i32 s3, s46
	s_cselect_b32 s0, s3, s0
	s_lshl_b32 s96, s0, 6
	s_lshl_b64 s[24:25], s[96:97], 1
	v_lshl_add_u64 v[128:129], v[162:163], 0, s[24:25]
	v_lshl_add_u64 v[130:131], v[172:173], 0, s[24:25]
	v_lshl_add_u64 v[132:133], v[174:175], 0, s[24:25]
	global_load_dwordx4 v[150:153], v[128:129], off
	s_nop 0
	global_load_dwordx4 v[128:131], v[130:131], off
	v_lshl_add_u64 v[134:135], v[176:177], 0, s[24:25]
	global_load_dwordx4 v[136:139], v[132:133], off
	global_load_dwordx4 v[146:149], v[134:135], off
	v_lshl_add_u64 v[132:133], v[164:165], 0, s[24:25]
	v_lshl_add_u64 v[142:143], v[178:179], 0, s[24:25]
	v_lshl_add_u64 v[154:155], v[180:181], 0, s[24:25]
	v_lshl_add_u64 v[156:157], v[182:183], 0, s[24:25]
	global_load_dwordx4 v[132:135], v[132:133], off
	s_nop 0
	global_load_dwordx4 v[142:145], v[142:143], off
	s_nop 0
	global_load_dwordx4 v[158:161], v[154:155], off
	s_nop 0
	global_load_dwordx4 v[154:157], v[156:157], off
	s_cmp_eq_u32 s46, s1
	s_mov_b32 s0, s1
	s_waitcnt lgkmcnt(0)
	s_barrier
	s_cbranch_scc0 .LBB0_62
	s_branch .LBB0_64

; #define PIN() do { asm volatile("" ::: "memory"); __builtin_amdgcn_sched_barrier(0); } while (0)
;     ...
;     for (int kt = kt0; kt < kt1; ++kt) {
;       const char* cur = smem + ((kt - kt0) & 1) * GBUF;
;       if (WM == 1) { GLOADG(kt + 1 < kt1 ? kt + 1 : kt); PIN(); }
;       const char* ab = cur + (wm * 32 * WM + l31) * GSTR + hh * 16;
;       const char* wb = cur + (256 + wn * 128 + l31) * GSTR + hh * 16;
;       bf16x8 tfA, tfA1, tfB, tfB1, wfA0, wfA1, wfA2, wfA3, wfB0, wfB1, wfB2, wfB3;
;     ...
;       if (WM == 1) {
;         LDFR(tfA, tfA1, wfA0, wfA1, wfA2, wfA3, 0);
;         LDFR(tfB, tfB1, wfB0, wfB1, wfB2, wfB3, 1);
;         PIN();
;         DOMM(tfA, tfA1, wfA0, wfA1, wfA2, wfA3);
;         PIN();
;         LDFR(tfA, tfA1, wfA0, wfA1, wfA2, wfA3, 2);
;         PIN();
;         DOMM(tfB, tfB1, wfB0, wfB1, wfB2, wfB3);
;         PIN();
;         LDFR(tfB, tfB1, wfB0, wfB1, wfB2, wfB3, 3);
;         PIN();
;         DOMM(tfA, tfA1, wfA0, wfA1, wfA2, wfA3);
;         DOMM(tfB, tfB1, wfB0, wfB1, wfB2, wfB3);
;       } else {
;         char* nb_ = smem + ((kt + 1 - kt0) & 1) * GBUF + lo;
;     ...
;         LDFR(tfA, tfA1, wfA0, wfA1, wfA2, wfA3, 0);
;         PIN();
;         DOMM(tfA, tfA1, wfA0, wfA1, wfA2, wfA3);
;         PIN();
;         LDFR(tfA, tfA1, wfA0, wfA1, wfA2, wfA3, 1);
;         PIN();
;         DOMM(tfA, tfA1, wfA0, wfA1, wfA2, wfA3);
;         PIN();
;         LDFR(tfA, tfA1, wfA0, wfA1, wfA2, wfA3, 2);
;         PIN();
;         MM2(0, tfA, wfA0, wfA1, 0, 1); PIN(); *(uint4*)(nb_) = ra0; PIN();
;         MM2(0, tfA, wfA2, wfA3, 2, 3); PIN(); *(uint4*)(nb_ + 64 * GSTR) = ra1; PIN();
;         MM2(1, tfA1, wfA0, wfA1, 0, 1); PIN(); *(uint4*)(nb_ + 128 * GSTR) = ra2; PIN();
;         MM2(1, tfA1, wfA2, wfA3, 2, 3); PIN(); *(uint4*)(nb_ + 192 * GSTR) = ra3; PIN();
;         LDFR(tfA, tfA1, wfA0, wfA1, wfA2, wfA3, 3);
;         PIN();
;         MM2(0, tfA, wfA0, wfA1, 0, 1); PIN(); *(uint4*)(nb_ + 256 * GSTR) = rw0; PIN();
;         MM2(0, tfA, wfA2, wfA3, 2, 3); PIN(); *(uint4*)(nb_ + 320 * GSTR) = rw1; PIN();
;         MM2(1, tfA1, wfA0, wfA1, 0, 1); PIN(); *(uint4*)(nb_ + 384 * GSTR) = rw2; PIN();
;         MM2(1, tfA1, wfA2, wfA3, 2, 3); PIN(); *(uint4*)(nb_ + 448 * GSTR) = rw3; PIN();
;         GLOADG(kt + 2 < kt1 ? kt + 2 : kt);
.LBB0_102:
	s_bitcmp1_b32 s27, 0
	s_cselect_b32 s24, 0x12000, 0
	s_add_i32 s24, s24, 0
	v_add3_u32 v140, s24, v189, v190
	v_add3_u32 v203, s24, v191, v190
	ds_read_b128 v[192:195], v140
	ds_read_b128 v[196:199], v140 offset:4608
	ds_read_b128 v[214:217], v203
	ds_read_b128 v[218:221], v203 offset:4608
	ds_read_b128 v[222:225], v203 offset:9216
	ds_read_b128 v[226:229], v203 offset:13824
	s_add_i32 s24, s27, 1
	s_bitcmp1_b32 s24, 0
	s_cselect_b32 s25, 0x12000, 0
	v_add_u32_e32 v206, s25, v188
	s_waitcnt lgkmcnt(2)
	v_mfma_f32_32x32x16_bf16 v[112:127], v[192:195], v[214:217], v[112:127]
	v_mfma_f32_32x32x16_bf16 v[96:111], v[192:195], v[218:221], v[96:111]
	s_waitcnt lgkmcnt(0)
	v_mfma_f32_32x32x16_bf16 v[80:95], v[192:195], v[222:225], v[80:95]
	v_mfma_f32_32x32x16_bf16 v[64:79], v[192:195], v[226:229], v[64:79]
	v_mfma_f32_32x32x16_bf16 v[48:63], v[196:199], v[214:217], v[48:63]
	v_mfma_f32_32x32x16_bf16 v[32:47], v[196:199], v[218:221], v[32:47]
	v_mfma_f32_32x32x16_bf16 v[16:31], v[196:199], v[222:225], v[16:31]
	v_mfma_f32_32x32x16_bf16 v[0:15], v[196:199], v[226:229], v[0:15]
	ds_read_b128 v[192:195], v140 offset:32
	ds_read_b128 v[196:199], v140 offset:4640
	ds_read_b128 v[214:217], v203 offset:32
	ds_read_b128 v[218:221], v203 offset:4640
	ds_read_b128 v[222:225], v203 offset:9248
	ds_read_b128 v[226:229], v203 offset:13856
	s_waitcnt lgkmcnt(2)
	v_mfma_f32_32x32x16_bf16 v[112:127], v[192:195], v[214:217], v[112:127]
	v_mfma_f32_32x32x16_bf16 v[96:111], v[192:195], v[218:221], v[96:111]
	s_waitcnt lgkmcnt(0)
	v_mfma_f32_32x32x16_bf16 v[80:95], v[192:195], v[222:225], v[80:95]
	v_mfma_f32_32x32x16_bf16 v[64:79], v[192:195], v[226:229], v[64:79]
	v_mfma_f32_32x32x16_bf16 v[48:63], v[196:199], v[214:217], v[48:63]
	v_mfma_f32_32x32x16_bf16 v[32:47], v[196:199], v[218:221], v[32:47]
	v_mfma_f32_32x32x16_bf16 v[16:31], v[196:199], v[222:225], v[16:31]
	v_mfma_f32_32x32x16_bf16 v[0:15], v[196:199], v[226:229], v[0:15]
	ds_read_b128 v[192:195], v140 offset:64
	ds_read_b128 v[196:199], v140 offset:4672
	ds_read_b128 v[214:217], v203 offset:64
	ds_read_b128 v[218:221], v203 offset:4672
	ds_read_b128 v[222:225], v203 offset:9280
	ds_read_b128 v[226:229], v203 offset:13888
	s_waitcnt lgkmcnt(2)
	v_mfma_f32_32x32x16_bf16 v[112:127], v[192:195], v[214:217], v[112:127]
	v_mfma_f32_32x32x16_bf16 v[96:111], v[192:195], v[218:221], v[96:111]
	s_waitcnt vmcnt(7)
	ds_write_b128 v206, v[158:161]
	s_waitcnt lgkmcnt(1)
	v_mfma_f32_32x32x16_bf16 v[80:95], v[192:195], v[222:225], v[80:95]
	v_mfma_f32_32x32x16_bf16 v[64:79], v[192:195], v[226:229], v[64:79]
	s_waitcnt vmcnt(6)
	ds_write_b128 v206, v[154:157] offset:9216
	v_mfma_f32_32x32x16_bf16 v[48:63], v[196:199], v[214:217], v[48:63]
	v_mfma_f32_32x32x16_bf16 v[32:47], v[196:199], v[218:221], v[32:47]
	s_waitcnt vmcnt(5)
	ds_write_b128 v206, v[150:153] offset:18432
	v_mfma_f32_32x32x16_bf16 v[16:31], v[196:199], v[222:225], v[16:31]
	v_mfma_f32_32x32x16_bf16 v[0:15], v[196:199], v[226:229], v[0:15]
	s_waitcnt vmcnt(4)
	ds_write_b128 v206, v[146:149] offset:27648
	ds_read_b128 v[146:149], v140 offset:96
	ds_read_b128 v[150:153], v140 offset:4704
	ds_read_b128 v[154:157], v203 offset:96
	ds_read_b128 v[158:161], v203 offset:4704
	ds_read_b128 v[192:195], v203 offset:9312
	ds_read_b128 v[196:199], v203 offset:13920
	s_waitcnt lgkmcnt(2)
	v_mfma_f32_32x32x16_bf16 v[112:127], v[146:149], v[154:157], v[112:127]
	v_mfma_f32_32x32x16_bf16 v[96:111], v[146:149], v[158:161], v[96:111]
	s_waitcnt vmcnt(3)
	ds_write_b128 v206, v[142:145] offset:36864
	s_waitcnt lgkmcnt(1)
	v_mfma_f32_32x32x16_bf16 v[80:95], v[146:149], v[192:195], v[80:95]
	v_mfma_f32_32x32x16_bf16 v[64:79], v[146:149], v[196:199], v[64:79]
	s_waitcnt vmcnt(2)
	ds_write_b128 v206, v[136:139] offset:46080
	v_mfma_f32_32x32x16_bf16 v[48:63], v[150:153], v[154:157], v[48:63]
	v_mfma_f32_32x32x16_bf16 v[32:47], v[150:153], v[158:161], v[32:47]
	s_waitcnt vmcnt(1)
	ds_write_b128 v206, v[132:135] offset:55296
	v_mfma_f32_32x32x16_bf16 v[16:31], v[150:153], v[192:195], v[16:31]
	v_mfma_f32_32x32x16_bf16 v[0:15], v[150:153], v[196:199], v[0:15]
	s_waitcnt vmcnt(0)
	ds_write_b128 v206, v[128:131] offset:64512
	s_add_i32 s25, s27, 2
	s_cmp_lt_u32 s25, s30
	s_cselect_b32 s25, s25, s27
	s_lshl_b32 s96, s25, 7
	v_lshl_add_u64 v[128:129], v[170:171], 0, s[96:97]
	v_lshl_add_u64 v[130:131], v[174:175], 0, s[96:97]
	global_load_dwordx4 v[158:161], v[128:129], off
	global_load_dwordx4 v[154:157], v[130:131], off
	v_lshl_add_u64 v[128:129], v[176:177], 0, s[96:97]
	v_lshl_add_u64 v[130:131], v[178:179], 0, s[96:97]
	global_load_dwordx4 v[150:153], v[128:129], off
	global_load_dwordx4 v[146:149], v[130:131], off
	v_lshl_add_u64 v[128:129], v[172:173], 0, s[96:97]
	v_lshl_add_u64 v[130:131], v[180:181], 0, s[96:97]
	global_load_dwordx4 v[142:145], v[128:129], off
	global_load_dwordx4 v[136:139], v[130:131], off
	v_lshl_add_u64 v[128:129], v[182:183], 0, s[96:97]
	v_lshl_add_u64 v[130:131], v[184:185], 0, s[96:97]
	global_load_dwordx4 v[132:135], v[128:129], off
	s_nop 0
	global_load_dwordx4 v[128:131], v[130:131], off
	s_cmp_ge_u32 s24, s30
	s_mov_b32 s27, s24
	s_waitcnt lgkmcnt(0)
	s_barrier
	s_cbranch_scc0 .LBB0_102

; #define PIN() do { asm volatile("" ::: "memory"); __builtin_amdgcn_sched_barrier(0); } while (0)
;     ...
;     for (int kt = kt0; kt < kt1; ++kt) {
;       const char* cur = smem + ((kt - kt0) & 1) * GBUF;
;       if (WM == 1) { GLOADG(kt + 1 < kt1 ? kt + 1 : kt); PIN(); }
;       const char* ab = cur + (wm * 32 * WM + l31) * GSTR + hh * 16;
;       const char* wb = cur + (256 + wn * 128 + l31) * GSTR + hh * 16;
;       bf16x8 tfA, tfA1, tfB, tfB1, wfA0, wfA1, wfA2, wfA3, wfB0, wfB1, wfB2, wfB3;
;     ...
;       if (WM == 1) {
;         LDFR(tfA, tfA1, wfA0, wfA1, wfA2, wfA3, 0);
;         LDFR(tfB, tfB1, wfB0, wfB1, wfB2, wfB3, 1);
;         PIN();
;         DOMM(tfA, tfA1, wfA0, wfA1, wfA2, wfA3);
;         PIN();
;         LDFR(tfA, tfA1, wfA0, wfA1, wfA2, wfA3, 2);
;         PIN();
;         DOMM(tfB, tfB1, wfB0, wfB1, wfB2, wfB3);
;         PIN();
;         LDFR(tfB, tfB1, wfB0, wfB1, wfB2, wfB3, 3);
;         PIN();
;         DOMM(tfA, tfA1, wfA0, wfA1, wfA2, wfA3);
;         DOMM(tfB, tfB1, wfB0, wfB1, wfB2, wfB3);
;       } else {
;         char* nb_ = smem + ((kt + 1 - kt0) & 1) * GBUF + lo;
;     ...
;         LDFR(tfA, tfA1, wfA0, wfA1, wfA2, wfA3, 0);
;         PIN();
;         DOMM(tfA, tfA1, wfA0, wfA1, wfA2, wfA3);
;         PIN();
;         LDFR(tfA, tfA1, wfA0, wfA1, wfA2, wfA3, 1);
;         PIN();
;         DOMM(tfA, tfA1, wfA0, wfA1, wfA2, wfA3);
;         PIN();
;         LDFR(tfA, tfA1, wfA0, wfA1, wfA2, wfA3, 2);
;         PIN();
;         MM2(0, tfA, wfA0, wfA1, 0, 1); PIN(); *(uint4*)(nb_) = ra0; PIN();
;         MM2(0, tfA, wfA2, wfA3, 2, 3); PIN(); *(uint4*)(nb_ + 64 * GSTR) = ra1; PIN();
;         MM2(1, tfA1, wfA0, wfA1, 0, 1); PIN(); *(uint4*)(nb_ + 128 * GSTR) = ra2; PIN();
;         MM2(1, tfA1, wfA2, wfA3, 2, 3); PIN(); *(uint4*)(nb_ + 192 * GSTR) = ra3; PIN();
;         LDFR(tfA, tfA1, wfA0, wfA1, wfA2, wfA3, 3);
;         PIN();
;         MM2(0, tfA, wfA0, wfA1, 0, 1); PIN(); *(uint4*)(nb_ + 256 * GSTR) = rw0; PIN();
;         MM2(0, tfA, wfA2, wfA3, 2, 3); PIN(); *(uint4*)(nb_ + 320 * GSTR) = rw1; PIN();
;         MM2(1, tfA1, wfA0, wfA1, 0, 1); PIN(); *(uint4*)(nb_ + 384 * GSTR) = rw2; PIN();
;         MM2(1, tfA1, wfA2, wfA3, 2, 3); PIN(); *(uint4*)(nb_ + 448 * GSTR) = rw3; PIN();
;         GLOADG(kt + 2 < kt1 ? kt + 2 : kt);
.LBB0_307:
	s_bitcmp1_b32 s0, 0
	s_cselect_b32 s1, 0x12000, 0
	s_add_i32 s1, s1, 0
	v_add3_u32 v140, s1, v196, v197
	v_add3_u32 v230, s1, v198, v197
	ds_read_b128 v[184:187], v140
	ds_read_b128 v[188:191], v140 offset:4608
	ds_read_b128 v[214:217], v230
	ds_read_b128 v[218:221], v230 offset:4608
	ds_read_b128 v[222:225], v230 offset:9216
	ds_read_b128 v[226:229], v230 offset:13824
	s_add_i32 s1, s0, 1
	s_bitcmp1_b32 s1, 0
	s_cselect_b32 s3, 0x12000, 0
	v_add_u32_e32 v231, s3, v195
	s_waitcnt lgkmcnt(2)
	v_mfma_f32_32x32x16_bf16 v[112:127], v[184:187], v[214:217], v[112:127]
	v_mfma_f32_32x32x16_bf16 v[96:111], v[184:187], v[218:221], v[96:111]
	s_waitcnt lgkmcnt(0)
	v_mfma_f32_32x32x16_bf16 v[80:95], v[184:187], v[222:225], v[80:95]
	v_mfma_f32_32x32x16_bf16 v[64:79], v[184:187], v[226:229], v[64:79]
	v_mfma_f32_32x32x16_bf16 v[48:63], v[188:191], v[214:217], v[48:63]
	v_mfma_f32_32x32x16_bf16 v[32:47], v[188:191], v[218:221], v[32:47]
	v_mfma_f32_32x32x16_bf16 v[16:31], v[188:191], v[222:225], v[16:31]
	v_mfma_f32_32x32x16_bf16 v[0:15], v[188:191], v[226:229], v[0:15]
	ds_read_b128 v[184:187], v140 offset:32
	ds_read_b128 v[188:191], v140 offset:4640
	ds_read_b128 v[214:217], v230 offset:32
	ds_read_b128 v[218:221], v230 offset:4640
	ds_read_b128 v[222:225], v230 offset:9248
	ds_read_b128 v[226:229], v230 offset:13856
	s_waitcnt lgkmcnt(2)
	v_mfma_f32_32x32x16_bf16 v[112:127], v[184:187], v[214:217], v[112:127]
	v_mfma_f32_32x32x16_bf16 v[96:111], v[184:187], v[218:221], v[96:111]
	s_waitcnt lgkmcnt(0)
	v_mfma_f32_32x32x16_bf16 v[80:95], v[184:187], v[222:225], v[80:95]
	v_mfma_f32_32x32x16_bf16 v[64:79], v[184:187], v[226:229], v[64:79]
	v_mfma_f32_32x32x16_bf16 v[48:63], v[188:191], v[214:217], v[48:63]
	v_mfma_f32_32x32x16_bf16 v[32:47], v[188:191], v[218:221], v[32:47]
	v_mfma_f32_32x32x16_bf16 v[16:31], v[188:191], v[222:225], v[16:31]
	v_mfma_f32_32x32x16_bf16 v[0:15], v[188:191], v[226:229], v[0:15]
	ds_read_b128 v[184:187], v140 offset:64
	ds_read_b128 v[188:191], v140 offset:4672
	ds_read_b128 v[214:217], v230 offset:64
	ds_read_b128 v[218:221], v230 offset:4672
	ds_read_b128 v[222:225], v230 offset:9280
	ds_read_b128 v[226:229], v230 offset:13888
	s_waitcnt lgkmcnt(2)
	v_mfma_f32_32x32x16_bf16 v[112:127], v[184:187], v[214:217], v[112:127]
	v_mfma_f32_32x32x16_bf16 v[96:111], v[184:187], v[218:221], v[96:111]
	s_waitcnt vmcnt(7)
	ds_write_b128 v231, v[150:153]
	s_waitcnt lgkmcnt(1)
	v_mfma_f32_32x32x16_bf16 v[80:95], v[184:187], v[222:225], v[80:95]
	v_mfma_f32_32x32x16_bf16 v[64:79], v[184:187], v[226:229], v[64:79]
	s_waitcnt vmcnt(6)
	ds_write_b128 v231, v[128:131] offset:9216
	v_mfma_f32_32x32x16_bf16 v[48:63], v[188:191], v[214:217], v[48:63]
	v_mfma_f32_32x32x16_bf16 v[32:47], v[188:191], v[218:221], v[32:47]
	s_waitcnt vmcnt(5)
	ds_write_b128 v231, v[136:139] offset:18432
	v_mfma_f32_32x32x16_bf16 v[16:31], v[188:191], v[222:225], v[16:31]
	v_mfma_f32_32x32x16_bf16 v[0:15], v[188:191], v[226:229], v[0:15]
	s_waitcnt vmcnt(4)
	ds_write_b128 v231, v[146:149] offset:27648
	ds_read_b128 v[128:131], v140 offset:96
	ds_read_b128 v[136:139], v140 offset:4704
	ds_read_b128 v[146:149], v230 offset:96
	ds_read_b128 v[150:153], v230 offset:4704
	ds_read_b128 v[184:187], v230 offset:9312
	ds_read_b128 v[188:191], v230 offset:13920
	s_waitcnt lgkmcnt(2)
	v_mfma_f32_32x32x16_bf16 v[112:127], v[128:131], v[146:149], v[112:127]
	v_mfma_f32_32x32x16_bf16 v[96:111], v[128:131], v[150:153], v[96:111]
	s_waitcnt vmcnt(3)
	ds_write_b128 v231, v[132:135] offset:36864
	s_waitcnt lgkmcnt(1)
	v_mfma_f32_32x32x16_bf16 v[80:95], v[128:131], v[184:187], v[80:95]
	v_mfma_f32_32x32x16_bf16 v[64:79], v[128:131], v[188:191], v[64:79]
	s_waitcnt vmcnt(2)
	ds_write_b128 v231, v[142:145] offset:46080
	v_mfma_f32_32x32x16_bf16 v[48:63], v[136:139], v[146:149], v[48:63]
	v_mfma_f32_32x32x16_bf16 v[32:47], v[136:139], v[150:153], v[32:47]
	s_waitcnt vmcnt(1)
	ds_write_b128 v231, v[158:161] offset:55296
	v_mfma_f32_32x32x16_bf16 v[16:31], v[136:139], v[184:187], v[16:31]
	v_mfma_f32_32x32x16_bf16 v[0:15], v[136:139], v[188:191], v[0:15]
	s_waitcnt vmcnt(0)
	ds_write_b128 v231, v[154:157] offset:64512
	s_add_i32 s3, s0, 2
	s_cmp_lt_i32 s3, s49
	s_cselect_b32 s0, s3, s0
	s_lshl_b32 s96, s0, 6
	s_lshl_b64 s[24:25], s[96:97], 1
	v_lshl_add_u64 v[128:129], v[162:163], 0, s[24:25]
	v_lshl_add_u64 v[130:131], v[172:173], 0, s[24:25]
	v_lshl_add_u64 v[132:133], v[174:175], 0, s[24:25]
	global_load_dwordx4 v[150:153], v[128:129], off
	s_nop 0
	global_load_dwordx4 v[128:131], v[130:131], off
	v_lshl_add_u64 v[134:135], v[176:177], 0, s[24:25]
	global_load_dwordx4 v[136:139], v[132:133], off
	global_load_dwordx4 v[146:149], v[134:135], off
	v_lshl_add_u64 v[132:133], v[164:165], 0, s[24:25]
	v_lshl_add_u64 v[142:143], v[178:179], 0, s[24:25]
	v_lshl_add_u64 v[154:155], v[180:181], 0, s[24:25]
	v_lshl_add_u64 v[156:157], v[182:183], 0, s[24:25]
	global_load_dwordx4 v[132:135], v[132:133], off
	s_nop 0
	global_load_dwordx4 v[142:145], v[142:143], off
	s_nop 0
	global_load_dwordx4 v[158:161], v[154:155], off
	s_nop 0
	global_load_dwordx4 v[154:157], v[156:157], off
	s_cmp_eq_u32 s49, s1
	s_mov_b32 s0, s1
	s_waitcnt lgkmcnt(0)
	s_barrier
	s_cbranch_scc0 .LBB0_307
	s_branch .LBB0_309

;     ...
;     for (int kt = kt0; kt < kt1; ++kt) {
;       const char* cur = smem + ((kt - kt0) & 1) * GBUF;
;       if (WM == 1) { GLOADG(kt + 1 < kt1 ? kt + 1 : kt); PIN(); }
;       const char* ab = cur + (wm * 32 * WM + l31) * GSTR + hh * 16;
;       const char* wb = cur + (256 + wn * 128 + l31) * GSTR + hh * 16;
;       bf16x8 tfA, tfA1, tfB, tfB1, wfA0, wfA1, wfA2, wfA3, wfB0, wfB1, wfB2, wfB3;
;     ...
;       if (WM == 1) {
;         LDFR(tfA, tfA1, wfA0, wfA1, wfA2, wfA3, 0);
;         LDFR(tfB, tfB1, wfB0, wfB1, wfB2, wfB3, 1);
;         PIN();
;         DOMM(tfA, tfA1, wfA0, wfA1, wfA2, wfA3);
;         PIN();
;         LDFR(tfA, tfA1, wfA0, wfA1, wfA2, wfA3, 2);
;         PIN();
;         DOMM(tfB, tfB1, wfB0, wfB1, wfB2, wfB3);
;         PIN();
;         LDFR(tfB, tfB1, wfB0, wfB1, wfB2, wfB3, 3);
;         PIN();
;         DOMM(tfA, tfA1, wfA0, wfA1, wfA2, wfA3);
;         DOMM(tfB, tfB1, wfB0, wfB1, wfB2, wfB3);
;       } else {
;         char* nb_ = smem + ((kt + 1 - kt0) & 1) * GBUF + lo;
;     ...
;         LDFR(tfA, tfA1, wfA0, wfA1, wfA2, wfA3, 0);
;         PIN();
;         DOMM(tfA, tfA1, wfA0, wfA1, wfA2, wfA3);
;         PIN();
;         LDFR(tfA, tfA1, wfA0, wfA1, wfA2, wfA3, 1);
;         PIN();
;         DOMM(tfA, tfA1, wfA0, wfA1, wfA2, wfA3);
;         PIN();
;         LDFR(tfA, tfA1, wfA0, wfA1, wfA2, wfA3, 2);
;         PIN();
;         MM2(0, tfA, wfA0, wfA1, 0, 1); PIN(); *(uint4*)(nb_) = ra0; PIN();
;         MM2(0, tfA, wfA2, wfA3, 2, 3); PIN(); *(uint4*)(nb_ + 64 * GSTR) = ra1; PIN();
;         MM2(1, tfA1, wfA0, wfA1, 0, 1); PIN(); *(uint4*)(nb_ + 128 * GSTR) = ra2; PIN();
;         MM2(1, tfA1, wfA2, wfA3, 2, 3); PIN(); *(uint4*)(nb_ + 192 * GSTR) = ra3; PIN();
;         LDFR(tfA, tfA1, wfA0, wfA1, wfA2, wfA3, 3);
;         PIN();
;         MM2(0, tfA, wfA0, wfA1, 0, 1); PIN(); *(uint4*)(nb_ + 256 * GSTR) = rw0; PIN();
;         MM2(0, tfA, wfA2, wfA3, 2, 3); PIN(); *(uint4*)(nb_ + 320 * GSTR) = rw1; PIN();
;         MM2(1, tfA1, wfA0, wfA1, 0, 1); PIN(); *(uint4*)(nb_ + 384 * GSTR) = rw2; PIN();
;         MM2(1, tfA1, wfA2, wfA3, 2, 3); PIN(); *(uint4*)(nb_ + 448 * GSTR) = rw3; PIN();
;         GLOADG(kt + 2 < kt1 ? kt + 2 : kt);
;   DI void operator()(f32x16 (&acc)[4], int tok0, int nt, int lane, bool part = false) const {
;     const int l31 = lane & 31, hh = lane >> 5;
.LBB0_889:
	s_bitcmp1_b32 s3, 0
	s_cselect_b32 s24, 0x12000, 0
	s_add_i32 s24, s24, 0
	v_add3_u32 v140, s24, v192, v193
	v_add3_u32 v197, s24, v194, v193
	ds_read_b128 v[214:217], v140
	ds_read_b128 v[218:221], v140 offset:4608
	ds_read_b128 v[222:225], v197
	ds_read_b128 v[226:229], v197 offset:4608
	ds_read_b128 v[230:233], v197 offset:9216
	ds_read_b128 v[234:237], v197 offset:13824
	s_add_i32 s24, s3, 1
	s_bitcmp1_b32 s24, 0
	s_cselect_b32 s25, 0x12000, 0
	v_add_u32_e32 v198, s25, v191
	s_waitcnt lgkmcnt(2)
	v_mfma_f32_32x32x16_bf16 v[112:127], v[222:225], v[214:217], v[112:127]
	v_mfma_f32_32x32x16_bf16 v[96:111], v[226:229], v[214:217], v[96:111]
	s_waitcnt lgkmcnt(0)
	v_mfma_f32_32x32x16_bf16 v[80:95], v[230:233], v[214:217], v[80:95]
	v_mfma_f32_32x32x16_bf16 v[64:79], v[234:237], v[214:217], v[64:79]
	v_mfma_f32_32x32x16_bf16 v[48:63], v[222:225], v[218:221], v[48:63]
	v_mfma_f32_32x32x16_bf16 v[32:47], v[226:229], v[218:221], v[32:47]
	v_mfma_f32_32x32x16_bf16 v[16:31], v[230:233], v[218:221], v[16:31]
	v_mfma_f32_32x32x16_bf16 v[0:15], v[234:237], v[218:221], v[0:15]
	ds_read_b128 v[214:217], v140 offset:32
	ds_read_b128 v[218:221], v140 offset:4640
	ds_read_b128 v[222:225], v197 offset:32
	ds_read_b128 v[226:229], v197 offset:4640
	ds_read_b128 v[230:233], v197 offset:9248
	ds_read_b128 v[234:237], v197 offset:13856
	s_waitcnt lgkmcnt(2)
	v_mfma_f32_32x32x16_bf16 v[112:127], v[222:225], v[214:217], v[112:127]
	v_mfma_f32_32x32x16_bf16 v[96:111], v[226:229], v[214:217], v[96:111]
	s_waitcnt lgkmcnt(0)
	v_mfma_f32_32x32x16_bf16 v[80:95], v[230:233], v[214:217], v[80:95]
	v_mfma_f32_32x32x16_bf16 v[64:79], v[234:237], v[214:217], v[64:79]
	v_mfma_f32_32x32x16_bf16 v[48:63], v[222:225], v[218:221], v[48:63]
	v_mfma_f32_32x32x16_bf16 v[32:47], v[226:229], v[218:221], v[32:47]
	v_mfma_f32_32x32x16_bf16 v[16:31], v[230:233], v[218:221], v[16:31]
	v_mfma_f32_32x32x16_bf16 v[0:15], v[234:237], v[218:221], v[0:15]
	ds_read_b128 v[214:217], v140 offset:64
	ds_read_b128 v[218:221], v140 offset:4672
	ds_read_b128 v[222:225], v197 offset:64
	ds_read_b128 v[226:229], v197 offset:4672
	ds_read_b128 v[230:233], v197 offset:9280
	ds_read_b128 v[234:237], v197 offset:13888
	s_waitcnt lgkmcnt(2)
	v_mfma_f32_32x32x16_bf16 v[112:127], v[222:225], v[214:217], v[112:127]
	v_mfma_f32_32x32x16_bf16 v[96:111], v[226:229], v[214:217], v[96:111]
	s_waitcnt vmcnt(7)
	ds_write_b128 v198, v[158:161]
	s_waitcnt lgkmcnt(1)
	v_mfma_f32_32x32x16_bf16 v[80:95], v[230:233], v[214:217], v[80:95]
	v_mfma_f32_32x32x16_bf16 v[64:79], v[234:237], v[214:217], v[64:79]
	s_waitcnt vmcnt(5)
	ds_write_b128 v198, v[154:157] offset:9216
	v_mfma_f32_32x32x16_bf16 v[48:63], v[222:225], v[218:221], v[48:63]
	v_mfma_f32_32x32x16_bf16 v[32:47], v[226:229], v[218:221], v[32:47]
	s_waitcnt vmcnt(4)
	ds_write_b128 v198, v[150:153] offset:18432
	v_mfma_f32_32x32x16_bf16 v[16:31], v[230:233], v[218:221], v[16:31]
	v_mfma_f32_32x32x16_bf16 v[0:15], v[234:237], v[218:221], v[0:15]
	s_waitcnt vmcnt(3)
	ds_write_b128 v198, v[146:149] offset:27648
	ds_read_b128 v[146:149], v140 offset:96
	ds_read_b128 v[150:153], v140 offset:4704
	ds_read_b128 v[154:157], v197 offset:96
	ds_read_b128 v[158:161], v197 offset:4704
	ds_read_b128 v[214:217], v197 offset:9312
	ds_read_b128 v[218:221], v197 offset:13920
	s_waitcnt lgkmcnt(2)
	v_mfma_f32_32x32x16_bf16 v[112:127], v[154:157], v[146:149], v[112:127]
	v_mfma_f32_32x32x16_bf16 v[96:111], v[158:161], v[146:149], v[96:111]
	ds_write_b128 v198, v[142:145] offset:36864
	s_waitcnt lgkmcnt(1)
	v_mfma_f32_32x32x16_bf16 v[80:95], v[214:217], v[146:149], v[80:95]
	v_mfma_f32_32x32x16_bf16 v[64:79], v[218:221], v[146:149], v[64:79]
	s_waitcnt vmcnt(2)
	ds_write_b128 v198, v[136:139] offset:46080
	v_mfma_f32_32x32x16_bf16 v[48:63], v[154:157], v[150:153], v[48:63]
	v_mfma_f32_32x32x16_bf16 v[32:47], v[158:161], v[150:153], v[32:47]
	s_waitcnt vmcnt(1)
	ds_write_b128 v198, v[132:135] offset:55296
	v_mfma_f32_32x32x16_bf16 v[16:31], v[214:217], v[150:153], v[16:31]
	v_mfma_f32_32x32x16_bf16 v[0:15], v[218:221], v[150:153], v[0:15]
	s_waitcnt vmcnt(0)
	ds_write_b128 v198, v[128:131] offset:64512
	s_add_i32 s25, s1, 0x80
	s_cmp_lt_u32 s3, 14
	s_cselect_b32 s96, s25, s1
	s_lshl_b64 s[38:39], s[96:97], 1
	v_lshl_add_u64 v[128:129], v[174:175], 0, s[38:39]
	v_lshl_add_u64 v[130:131], v[178:179], 0, s[38:39]
	global_load_dwordx4 v[158:161], v[128:129], off
	global_load_dwordx4 v[154:157], v[130:131], off
	v_lshl_add_u64 v[128:129], v[180:181], 0, s[38:39]
	v_lshl_add_u64 v[130:131], v[182:183], 0, s[38:39]
	global_load_dwordx4 v[150:153], v[128:129], off
	global_load_dwordx4 v[146:149], v[130:131], off
	v_lshl_add_u64 v[128:129], v[176:177], 0, s[38:39]
	v_lshl_add_u64 v[130:131], v[184:185], 0, s[38:39]
	global_load_dwordx4 v[142:145], v[128:129], off
	global_load_dwordx4 v[136:139], v[130:131], off
	v_lshl_add_u64 v[128:129], v[186:187], 0, s[38:39]
	v_lshl_add_u64 v[130:131], v[188:189], 0, s[38:39]
	global_load_dwordx4 v[132:135], v[128:129], off
	s_nop 0
	global_load_dwordx4 v[128:131], v[130:131], off
	s_add_i32 s1, s1, 64
	s_cmp_eq_u32 s24, 16
	s_mov_b32 s3, s24
	s_waitcnt lgkmcnt(0)
	s_barrier
	s_cbranch_scc0 .LBB0_889
	s_waitcnt vmcnt(6)
	v_lshl_or_b32 v155, s28, 8, v190
	v_lshl_add_u32 v154, s0, 1, v171
	v_readfirstlane_b32 s0, v155
	s_mul_hi_i32 s1, s0, 0x3e0f83e1
	s_lshr_b32 s24, s1, 31
	s_ashr_i32 s37, s1, 11
	s_add_i32 s37, s37, s24
	v_readfirstlane_b32 s3, v154
	s_mul_i32 s1, s37, 0xffffdf00
	s_waitcnt vmcnt(0)
	v_add_u32_e32 v128, s0, v173
	v_add_u32_e32 v138, s1, v128
	s_cmp_gt_i32 s3, 15
	s_mov_b64 s[0:1], -1
	s_cbranch_scc0 .LBB0_892
; DI unsigned short f2bf(float x) { return (unsigned short)(pk2(x, 0.f) & 0xffffu); }
; DI int crow(int i, int h) { return (i & 3) + 8 * (i >> 2) + 4 * h; }
; DI void vt_store(f32x16 (&acc)[4], bf16_t* vt  , int pos0, int hh) {
;   const int kq = pos0 & 15, pos = (pos0 & ~15) | (8 * ((kq >> 2) & 1) + (kq & 3) + 4 * (kq >> 3));
; #pragma unroll
;   for (int nb = 0; nb < 4; ++nb)
; #pragma unroll
;     for (int i = 0; i < 16; ++i) vt[(size_t)(nb * 32 + crow(i, hh)) * PL + pos] = f2bf(acc[nb][i]);
; }
;   DI void operator()(f32x16 (&acc)[4], int tok0, int nt, int lane, bool part = false) const {
;     ...
;     } else {
;       vt_store(acc, (bf16_t*)(ws + DF_VT) + (size_t)(b * 8 + (nt - 16)) * 128 * PL, pos, hh);
	s_lshl_b32 s0, s37, 3
	s_add_i32 s0, s3, s0
	s_add_i32 s0, s0, -16
	v_lshlrev_b32_e32 v129, 1, v128
	v_lshrrev_b32_e32 v128, 1, v128
	s_mul_hi_i32 s1, s0, 0x210000
	s_mul_i32 s0, s0, 0x210000
	v_readlane_b32 s24, v252, 32
	v_and_b32_e32 v129, 8, v129
	v_and_b32_e32 v128, 4, v128
	v_and_b32_e32 v130, -13, v138
	s_add_u32 s0, s24, s0
	v_readlane_b32 s24, v252, 33
	v_or3_b32 v128, v128, v129, v130
	s_addc_u32 s1, s24, s1
	v_ashrrev_i32_e32 v129, 31, v128
	v_lshl_add_u64 v[128:129], v[128:129], 1, s[0:1]
	v_cvt_pk_bf16_f32 v130, v112, s0
	v_lshl_add_u64 v[128:129], v[128:129], 0, v[168:169]
	v_cvt_pk_bf16_f32 v132, v113, s0
	s_movk_i32 s0, 0x4000
	global_store_short v[128:129], v130, off
	v_add_co_u32_e32 v130, vcc, s0, v128
	s_nop 1
	v_addc_co_u32_e32 v131, vcc, 0, v129, vcc
	global_store_short v[130:131], v132, off offset:512
	v_cvt_pk_bf16_f32 v132, v114, s0
	s_mov_b32 s0, 0x8000
	v_add_co_u32_e32 v130, vcc, s0, v128
	s_nop 1
	v_addc_co_u32_e32 v131, vcc, 0, v129, vcc
	global_store_short v[130:131], v132, off offset:1024
	v_add_co_u32_e32 v130, vcc, s2, v128
	v_cvt_pk_bf16_f32 v132, v115, s0
	s_nop 0
	v_addc_co_u32_e32 v131, vcc, 0, v129, vcc
	global_store_short v[130:131], v132, off offset:1536
	v_cvt_pk_bf16_f32 v132, v116, s0
	s_mov_b32 s0, 0x21000
	v_add_co_u32_e32 v130, vcc, s0, v128
	s_nop 1
	v_addc_co_u32_e32 v131, vcc, 0, v129, vcc
	global_store_short v[130:131], v132, off
	v_cvt_pk_bf16_f32 v132, v117, s0
	s_mov_b32 s0, 0x25000
	v_add_co_u32_e32 v130, vcc, s0, v128
	s_nop 1
	v_addc_co_u32_e32 v131, vcc, 0, v129, vcc
	global_store_short v[130:131], v132, off offset:512
	v_cvt_pk_bf16_f32 v132, v118, s0
	s_mov_b32 s0, 0x29000
	v_add_co_u32_e32 v130, vcc, s0, v128
	s_nop 1
	v_addc_co_u32_e32 v131, vcc, 0, v129, vcc
	global_store_short v[130:131], v132, off offset:1024
	v_cvt_pk_bf16_f32 v132, v119, s0
	s_mov_b32 s0, 0x2d000
	v_add_co_u32_e32 v130, vcc, s0, v128
	s_nop 1
	v_addc_co_u32_e32 v131, vcc, 0, v129, vcc
	global_store_short v[130:131], v132, off offset:1536
	v_cvt_pk_bf16_f32 v132, v120, s0
	s_mov_b32 s0, 0x42000
	v_add_co_u32_e32 v130, vcc, s0, v128
	s_nop 1
	v_addc_co_u32_e32 v131, vcc, 0, v129, vcc
	global_store_short v[130:131], v132, off
	v_cvt_pk_bf16_f32 v132, v121, s0
	s_mov_b32 s0, 0x46000
	v_add_co_u32_e32 v130, vcc, s0, v128
	s_nop 1
	v_addc_co_u32_e32 v131, vcc, 0, v129, vcc
	global_store_short v[130:131], v132, off offset:512
	v_cvt_pk_bf16_f32 v132, v122, s0
	s_mov_b32 s0, 0x4a000
	v_add_co_u32_e32 v130, vcc, s0, v128
	s_nop 1
	v_addc_co_u32_e32 v131, vcc, 0, v129, vcc
	global_store_short v[130:131], v132, off offset:1024
	v_cvt_pk_bf16_f32 v132, v123, s0
	s_mov_b32 s0, 0x4e000
	v_add_co_u32_e32 v130, vcc, s0, v128
	s_nop 1
	v_addc_co_u32_e32 v131, vcc, 0, v129, vcc
	global_store_short v[130:131], v132, off offset:1536
	v_cvt_pk_bf16_f32 v132, v124, s0
	s_mov_b32 s0, 0x63000
	v_add_co_u32_e32 v130, vcc, s0, v128
	s_nop 1
	v_addc_co_u32_e32 v131, vcc, 0, v129, vcc
	global_store_short v[130:131], v132, off
	v_cvt_pk_bf16_f32 v132, v125, s0
	s_mov_b32 s0, 0x67000
	v_add_co_u32_e32 v130, vcc, s0, v128
	s_nop 1
	v_addc_co_u32_e32 v131, vcc, 0, v129, vcc
	global_store_short v[130:131], v132, off offset:512
	v_cvt_pk_bf16_f32 v132, v126, s0
	s_mov_b32 s0, 0x6b000
	v_add_co_u32_e32 v130, vcc, s0, v128
	s_nop 1
	v_addc_co_u32_e32 v131, vcc, 0, v129, vcc
	global_store_short v[130:131], v132, off offset:1024
	v_cvt_pk_bf16_f32 v132, v127, s0
	s_mov_b32 s0, 0x6f000
	v_add_co_u32_e32 v130, vcc, s0, v128
	s_nop 1
	v_addc_co_u32_e32 v131, vcc, 0, v129, vcc
	global_store_short v[130:131], v132, off offset:1536
	v_add_co_u32_e32 v130, vcc, s4, v128
	v_cvt_pk_bf16_f32 v132, v96, s0
	s_nop 0
	v_addc_co_u32_e32 v131, vcc, 0, v129, vcc
	global_store_short v[130:131], v132, off
	v_cvt_pk_bf16_f32 v132, v97, s0
	s_mov_b32 s0, 0x88000
	v_add_co_u32_e32 v130, vcc, s0, v128
	s_nop 1
	v_addc_co_u32_e32 v131, vcc, 0, v129, vcc
	global_store_short v[130:131], v132, off offset:512
	v_cvt_pk_bf16_f32 v132, v98, s0
	s_mov_b32 s0, 0x8c000
	v_add_co_u32_e32 v130, vcc, s0, v128
	s_nop 1
	v_addc_co_u32_e32 v131, vcc, 0, v129, vcc
	global_store_short v[130:131], v132, off offset:1024
	v_cvt_pk_bf16_f32 v132, v99, s0
	s_mov_b32 s0, 0x90000
	v_add_co_u32_e32 v130, vcc, s0, v128
	s_nop 1
	v_addc_co_u32_e32 v131, vcc, 0, v129, vcc
	global_store_short v[130:131], v132, off offset:1536
	v_cvt_pk_bf16_f32 v132, v100, s0
	s_mov_b32 s0, 0xa5000
	v_add_co_u32_e32 v130, vcc, s0, v128
	s_nop 1
	v_addc_co_u32_e32 v131, vcc, 0, v129, vcc
	global_store_short v[130:131], v132, off
	v_cvt_pk_bf16_f32 v132, v101, s0
	s_mov_b32 s0, 0xa9000
	v_add_co_u32_e32 v130, vcc, s0, v128
	s_nop 1
	v_addc_co_u32_e32 v131, vcc, 0, v129, vcc
	global_store_short v[130:131], v132, off offset:512
	v_cvt_pk_bf16_f32 v132, v102, s0
	s_mov_b32 s0, 0xad000
	v_add_co_u32_e32 v130, vcc, s0, v128
	s_nop 1
	v_addc_co_u32_e32 v131, vcc, 0, v129, vcc
	global_store_short v[130:131], v132, off offset:1024
	v_cvt_pk_bf16_f32 v132, v103, s0
	s_mov_b32 s0, 0xb1000
	v_add_co_u32_e32 v130, vcc, s0, v128
	s_nop 1
	v_addc_co_u32_e32 v131, vcc, 0, v129, vcc
	global_store_short v[130:131], v132, off offset:1536
	v_cvt_pk_bf16_f32 v132, v104, s0
	s_mov_b32 s0, 0xc6000
	v_add_co_u32_e32 v130, vcc, s0, v128
	s_nop 1
	v_addc_co_u32_e32 v131, vcc, 0, v129, vcc
	global_store_short v[130:131], v132, off
	v_cvt_pk_bf16_f32 v132, v105, s0
	s_mov_b32 s0, 0xca000
	v_add_co_u32_e32 v130, vcc, s0, v128
	s_nop 1
	v_addc_co_u32_e32 v131, vcc, 0, v129, vcc
	global_store_short v[130:131], v132, off offset:512
	v_cvt_pk_bf16_f32 v132, v106, s0
	s_mov_b32 s0, 0xce000
	v_add_co_u32_e32 v130, vcc, s0, v128
	s_nop 1
; DI unsigned short f2bf(float x) { return (unsigned short)(pk2(x, 0.f) & 0xffffu); }
; DI int crow(int i, int h) { return (i & 3) + 8 * (i >> 2) + 4 * h; }
; DI void vt_store(f32x16 (&acc)[4], bf16_t* vt  , int pos0, int hh) {
;   const int kq = pos0 & 15, pos = (pos0 & ~15) | (8 * ((kq >> 2) & 1) + (kq & 3) + 4 * (kq >> 3));
; #pragma unroll
;   for (int nb = 0; nb < 4; ++nb)
; #pragma unroll
;     for (int i = 0; i < 16; ++i) vt[(size_t)(nb * 32 + crow(i, hh)) * PL + pos] = f2bf(acc[nb][i]);
; }
	v_addc_co_u32_e32 v131, vcc, 0, v129, vcc
	global_store_short v[130:131], v132, off offset:1024
	v_cvt_pk_bf16_f32 v132, v107, s0
	s_mov_b32 s0, 0xd2000
	v_add_co_u32_e32 v130, vcc, s0, v128
	s_nop 1
	v_addc_co_u32_e32 v131, vcc, 0, v129, vcc
	global_store_short v[130:131], v132, off offset:1536
	v_cvt_pk_bf16_f32 v132, v108, s0
	s_mov_b32 s0, 0xe7000
	v_add_co_u32_e32 v130, vcc, s0, v128
	s_nop 1
	v_addc_co_u32_e32 v131, vcc, 0, v129, vcc
	global_store_short v[130:131], v132, off
	v_cvt_pk_bf16_f32 v132, v109, s0
	s_mov_b32 s0, 0xeb000
	v_add_co_u32_e32 v130, vcc, s0, v128
	s_nop 1
	v_addc_co_u32_e32 v131, vcc, 0, v129, vcc
	global_store_short v[130:131], v132, off offset:512
	v_cvt_pk_bf16_f32 v132, v110, s0
	s_mov_b32 s0, 0xef000
	v_add_co_u32_e32 v130, vcc, s0, v128
	s_nop 1
	v_addc_co_u32_e32 v131, vcc, 0, v129, vcc
	global_store_short v[130:131], v132, off offset:1024
	v_cvt_pk_bf16_f32 v132, v111, s0
	s_mov_b32 s0, 0xf3000
	v_add_co_u32_e32 v130, vcc, s0, v128
	s_nop 1
	v_addc_co_u32_e32 v131, vcc, 0, v129, vcc
	global_store_short v[130:131], v132, off offset:1536
	v_cvt_pk_bf16_f32 v132, v80, s0
	s_mov_b32 s0, 0x108000
	v_add_co_u32_e32 v130, vcc, s0, v128
	s_nop 1
	v_addc_co_u32_e32 v131, vcc, 0, v129, vcc
	global_store_short v[130:131], v132, off
	v_cvt_pk_bf16_f32 v132, v81, s0
	s_mov_b32 s0, 0x10c000
	v_add_co_u32_e32 v130, vcc, s0, v128
	s_nop 1
	v_addc_co_u32_e32 v131, vcc, 0, v129, vcc
	global_store_short v[130:131], v132, off offset:512
	v_cvt_pk_bf16_f32 v132, v82, s0
	s_mov_b32 s0, 0x110000
	v_add_co_u32_e32 v130, vcc, s0, v128
	s_nop 1
	v_addc_co_u32_e32 v131, vcc, 0, v129, vcc
	global_store_short v[130:131], v132, off offset:1024
	v_cvt_pk_bf16_f32 v132, v83, s0
	s_mov_b32 s0, 0x114000
	v_add_co_u32_e32 v130, vcc, s0, v128
	s_nop 1
	v_addc_co_u32_e32 v131, vcc, 0, v129, vcc
	global_store_short v[130:131], v132, off offset:1536
	v_cvt_pk_bf16_f32 v132, v84, s0
	s_mov_b32 s0, 0x129000
	v_add_co_u32_e32 v130, vcc, s0, v128
	s_nop 1
	v_addc_co_u32_e32 v131, vcc, 0, v129, vcc
	global_store_short v[130:131], v132, off
	v_cvt_pk_bf16_f32 v132, v85, s0
	s_mov_b32 s0, 0x12d000
	v_add_co_u32_e32 v130, vcc, s0, v128
	s_nop 1
	v_addc_co_u32_e32 v131, vcc, 0, v129, vcc
	global_store_short v[130:131], v132, off offset:512
	v_cvt_pk_bf16_f32 v132, v86, s0
	s_mov_b32 s0, 0x131000
	v_add_co_u32_e32 v130, vcc, s0, v128
	s_nop 1
	v_addc_co_u32_e32 v131, vcc, 0, v129, vcc
	global_store_short v[130:131], v132, off offset:1024
	v_cvt_pk_bf16_f32 v132, v87, s0
	s_mov_b32 s0, 0x135000
	v_add_co_u32_e32 v130, vcc, s0, v128
	s_nop 1
	v_addc_co_u32_e32 v131, vcc, 0, v129, vcc
	global_store_short v[130:131], v132, off offset:1536
	v_cvt_pk_bf16_f32 v132, v88, s0
	s_mov_b32 s0, 0x14a000
	v_add_co_u32_e32 v130, vcc, s0, v128
	s_nop 1
	v_addc_co_u32_e32 v131, vcc, 0, v129, vcc
	global_store_short v[130:131], v132, off
	v_cvt_pk_bf16_f32 v132, v89, s0
	s_mov_b32 s0, 0x14e000
	v_add_co_u32_e32 v130, vcc, s0, v128
	s_nop 1
	v_addc_co_u32_e32 v131, vcc, 0, v129, vcc
	global_store_short v[130:131], v132, off offset:512
	v_cvt_pk_bf16_f32 v132, v90, s0
	s_mov_b32 s0, 0x152000
	v_add_co_u32_e32 v130, vcc, s0, v128
	s_nop 1
	v_addc_co_u32_e32 v131, vcc, 0, v129, vcc
	global_store_short v[130:131], v132, off offset:1024
	v_cvt_pk_bf16_f32 v132, v91, s0
	s_mov_b32 s0, 0x156000
	v_add_co_u32_e32 v130, vcc, s0, v128
	s_nop 1
	v_addc_co_u32_e32 v131, vcc, 0, v129, vcc
	global_store_short v[130:131], v132, off offset:1536
	v_cvt_pk_bf16_f32 v132, v92, s0
	s_mov_b32 s0, 0x16b000
	v_add_co_u32_e32 v130, vcc, s0, v128
	s_nop 1
	v_addc_co_u32_e32 v131, vcc, 0, v129, vcc
	global_store_short v[130:131], v132, off
	v_cvt_pk_bf16_f32 v132, v93, s0
; DI unsigned short f2bf(float x) { return (unsigned short)(pk2(x, 0.f) & 0xffffu); }
; DI int crow(int i, int h) { return (i & 3) + 8 * (i >> 2) + 4 * h; }
; DI void vt_store(f32x16 (&acc)[4], bf16_t* vt  , int pos0, int hh) {
;   const int kq = pos0 & 15, pos = (pos0 & ~15) | (8 * ((kq >> 2) & 1) + (kq & 3) + 4 * (kq >> 3));
; #pragma unroll
;   for (int nb = 0; nb < 4; ++nb)
; #pragma unroll
;     for (int i = 0; i < 16; ++i) vt[(size_t)(nb * 32 + crow(i, hh)) * PL + pos] = f2bf(acc[nb][i]);
; }
	s_mov_b32 s0, 0x16f000
	v_add_co_u32_e32 v130, vcc, s0, v128
	s_nop 1
	v_addc_co_u32_e32 v131, vcc, 0, v129, vcc
	global_store_short v[130:131], v132, off offset:512
	v_cvt_pk_bf16_f32 v132, v94, s0
	s_mov_b32 s0, 0x173000
	v_add_co_u32_e32 v130, vcc, s0, v128
	s_nop 1
	v_addc_co_u32_e32 v131, vcc, 0, v129, vcc
	global_store_short v[130:131], v132, off offset:1024
	v_cvt_pk_bf16_f32 v132, v95, s0
	s_mov_b32 s0, 0x177000
	v_add_co_u32_e32 v130, vcc, s0, v128
	s_nop 1
	v_addc_co_u32_e32 v131, vcc, 0, v129, vcc
	global_store_short v[130:131], v132, off offset:1536
	v_cvt_pk_bf16_f32 v132, v64, s0
	s_mov_b32 s0, 0x18c000
	v_add_co_u32_e32 v130, vcc, s0, v128
	s_nop 1
	v_addc_co_u32_e32 v131, vcc, 0, v129, vcc
	global_store_short v[130:131], v132, off
	v_cvt_pk_bf16_f32 v132, v65, s0
	s_mov_b32 s0, 0x190000
	v_add_co_u32_e32 v130, vcc, s0, v128
	s_nop 1
	v_addc_co_u32_e32 v131, vcc, 0, v129, vcc
	global_store_short v[130:131], v132, off offset:512
	v_cvt_pk_bf16_f32 v132, v66, s0
	s_mov_b32 s0, 0x194000
	v_add_co_u32_e32 v130, vcc, s0, v128
	s_nop 1
	v_addc_co_u32_e32 v131, vcc, 0, v129, vcc
	global_store_short v[130:131], v132, off offset:1024
	v_cvt_pk_bf16_f32 v132, v67, s0
	s_mov_b32 s0, 0x198000
	v_add_co_u32_e32 v130, vcc, s0, v128
	s_nop 1
	v_addc_co_u32_e32 v131, vcc, 0, v129, vcc
	global_store_short v[130:131], v132, off offset:1536
	v_cvt_pk_bf16_f32 v132, v68, s0
	s_mov_b32 s0, 0x1ad000
	v_add_co_u32_e32 v130, vcc, s0, v128
	s_nop 1
	v_addc_co_u32_e32 v131, vcc, 0, v129, vcc
	global_store_short v[130:131], v132, off
	v_cvt_pk_bf16_f32 v132, v69, s0
	s_mov_b32 s0, 0x1b1000
	v_add_co_u32_e32 v130, vcc, s0, v128
	s_nop 1
	v_addc_co_u32_e32 v131, vcc, 0, v129, vcc
	global_store_short v[130:131], v132, off offset:512
	v_cvt_pk_bf16_f32 v132, v70, s0
	s_mov_b32 s0, 0x1b5000
	v_add_co_u32_e32 v130, vcc, s0, v128
	s_nop 1
	v_addc_co_u32_e32 v131, vcc, 0, v129, vcc
	global_store_short v[130:131], v132, off offset:1024
	v_cvt_pk_bf16_f32 v132, v71, s0
	s_mov_b32 s0, 0x1b9000
	v_add_co_u32_e32 v130, vcc, s0, v128
	s_nop 1
	v_addc_co_u32_e32 v131, vcc, 0, v129, vcc
	global_store_short v[130:131], v132, off offset:1536
	v_cvt_pk_bf16_f32 v132, v72, s0
	s_mov_b32 s0, 0x1ce000
	v_add_co_u32_e32 v130, vcc, s0, v128
	s_nop 1
	v_addc_co_u32_e32 v131, vcc, 0, v129, vcc
	global_store_short v[130:131], v132, off
	v_cvt_pk_bf16_f32 v132, v73, s0
	s_mov_b32 s0, 0x1d2000
	v_add_co_u32_e32 v130, vcc, s0, v128
	s_nop 1
	v_addc_co_u32_e32 v131, vcc, 0, v129, vcc
	global_store_short v[130:131], v132, off offset:512
	v_cvt_pk_bf16_f32 v132, v74, s0
	s_mov_b32 s0, 0x1d6000
	v_add_co_u32_e32 v130, vcc, s0, v128
	s_nop 1
	v_addc_co_u32_e32 v131, vcc, 0, v129, vcc
	global_store_short v[130:131], v132, off offset:1024
	v_cvt_pk_bf16_f32 v132, v75, s0
	s_mov_b32 s0, 0x1da000
	v_add_co_u32_e32 v130, vcc, s0, v128
	s_nop 1
	v_addc_co_u32_e32 v131, vcc, 0, v129, vcc
	global_store_short v[130:131], v132, off offset:1536
	v_cvt_pk_bf16_f32 v132, v76, s0
	s_mov_b32 s0, 0x1ef000
	v_add_co_u32_e32 v130, vcc, s0, v128
	s_nop 1
	v_addc_co_u32_e32 v131, vcc, 0, v129, vcc
	global_store_short v[130:131], v132, off
	v_add_co_u32_e32 v130, vcc, 0x1f3000, v128
	v_cvt_pk_bf16_f32 v132, v77, s0
	s_nop 0
	v_addc_co_u32_e32 v131, vcc, 0, v129, vcc
	global_store_short v[130:131], v132, off offset:512
	v_add_co_u32_e32 v130, vcc, 0x1f7000, v128
	v_cvt_pk_bf16_f32 v132, v78, s0
	s_nop 0
	v_addc_co_u32_e32 v131, vcc, 0, v129, vcc
	v_add_co_u32_e32 v128, vcc, 0x1fb000, v128
	global_store_short v[130:131], v132, off offset:1024
	v_cvt_pk_bf16_f32 v130, v79, s0
	v_addc_co_u32_e32 v129, vcc, 0, v129, vcc
	global_store_short v[128:129], v130, off offset:1536
	s_mov_b64 s[0:1], 0

; #define PIN() do { asm volatile("" ::: "memory"); __builtin_amdgcn_sched_barrier(0); } while (0)
;     ...
;     for (int kt = kt0; kt < kt1; ++kt) {
;       const char* cur = smem + ((kt - kt0) & 1) * GBUF;
;       if (WM == 1) { GLOADG(kt + 1 < kt1 ? kt + 1 : kt); PIN(); }
;       const char* ab = cur + (wm * 32 * WM + l31) * GSTR + hh * 16;
;       const char* wb = cur + (256 + wn * 128 + l31) * GSTR + hh * 16;
;       bf16x8 tfA, tfA1, tfB, tfB1, wfA0, wfA1, wfA2, wfA3, wfB0, wfB1, wfB2, wfB3;
;     ...
;       if (WM == 1) {
;         LDFR(tfA, tfA1, wfA0, wfA1, wfA2, wfA3, 0);
;         LDFR(tfB, tfB1, wfB0, wfB1, wfB2, wfB3, 1);
;         PIN();
;         DOMM(tfA, tfA1, wfA0, wfA1, wfA2, wfA3);
;         PIN();
;         LDFR(tfA, tfA1, wfA0, wfA1, wfA2, wfA3, 2);
;         PIN();
;         DOMM(tfB, tfB1, wfB0, wfB1, wfB2, wfB3);
;         PIN();
;         LDFR(tfB, tfB1, wfB0, wfB1, wfB2, wfB3, 3);
;         PIN();
;         DOMM(tfA, tfA1, wfA0, wfA1, wfA2, wfA3);
;         DOMM(tfB, tfB1, wfB0, wfB1, wfB2, wfB3);
;       } else {
;         char* nb_ = smem + ((kt + 1 - kt0) & 1) * GBUF + lo;
;     ...
;         LDFR(tfA, tfA1, wfA0, wfA1, wfA2, wfA3, 0);
;         PIN();
;         DOMM(tfA, tfA1, wfA0, wfA1, wfA2, wfA3);
;         PIN();
;         LDFR(tfA, tfA1, wfA0, wfA1, wfA2, wfA3, 1);
;         PIN();
;         DOMM(tfA, tfA1, wfA0, wfA1, wfA2, wfA3);
;         PIN();
;         LDFR(tfA, tfA1, wfA0, wfA1, wfA2, wfA3, 2);
;         PIN();
;         MM2(0, tfA, wfA0, wfA1, 0, 1); PIN(); *(uint4*)(nb_) = ra0; PIN();
;         MM2(0, tfA, wfA2, wfA3, 2, 3); PIN(); *(uint4*)(nb_ + 64 * GSTR) = ra1; PIN();
;         MM2(1, tfA1, wfA0, wfA1, 0, 1); PIN(); *(uint4*)(nb_ + 128 * GSTR) = ra2; PIN();
;         MM2(1, tfA1, wfA2, wfA3, 2, 3); PIN(); *(uint4*)(nb_ + 192 * GSTR) = ra3; PIN();
;         LDFR(tfA, tfA1, wfA0, wfA1, wfA2, wfA3, 3);
;         PIN();
;         MM2(0, tfA, wfA0, wfA1, 0, 1); PIN(); *(uint4*)(nb_ + 256 * GSTR) = rw0; PIN();
;         MM2(0, tfA, wfA2, wfA3, 2, 3); PIN(); *(uint4*)(nb_ + 320 * GSTR) = rw1; PIN();
;         MM2(1, tfA1, wfA0, wfA1, 0, 1); PIN(); *(uint4*)(nb_ + 384 * GSTR) = rw2; PIN();
;         MM2(1, tfA1, wfA2, wfA3, 2, 3); PIN(); *(uint4*)(nb_ + 448 * GSTR) = rw3; PIN();
;         GLOADG(kt + 2 < kt1 ? kt + 2 : kt);
.LBB0_910:
	s_bitcmp1_b32 s24, 0
	s_cselect_b32 s25, 0x12000, 0
	s_add_i32 s25, s25, 0
	v_add3_u32 v191, s25, v187, v188
	v_add3_u32 v230, s25, v189, v188
	ds_read_b128 v[192:195], v191
	ds_read_b128 v[196:199], v191 offset:4608
	ds_read_b128 v[214:217], v230
	ds_read_b128 v[218:221], v230 offset:4608
	ds_read_b128 v[222:225], v230 offset:9216
	ds_read_b128 v[226:229], v230 offset:13824
	s_add_i32 s25, s24, 1
	s_bitcmp1_b32 s25, 0
	s_cselect_b32 s27, 0x12000, 0
	v_add_u32_e32 v231, s27, v140
	s_waitcnt lgkmcnt(2)
	v_mfma_f32_32x32x16_bf16 v[112:127], v[192:195], v[214:217], v[112:127]
	v_mfma_f32_32x32x16_bf16 v[96:111], v[192:195], v[218:221], v[96:111]
	s_waitcnt lgkmcnt(0)
	v_mfma_f32_32x32x16_bf16 v[80:95], v[192:195], v[222:225], v[80:95]
	v_mfma_f32_32x32x16_bf16 v[64:79], v[192:195], v[226:229], v[64:79]
	v_mfma_f32_32x32x16_bf16 v[48:63], v[196:199], v[214:217], v[48:63]
	v_mfma_f32_32x32x16_bf16 v[32:47], v[196:199], v[218:221], v[32:47]
	v_mfma_f32_32x32x16_bf16 v[16:31], v[196:199], v[222:225], v[16:31]
	v_mfma_f32_32x32x16_bf16 v[0:15], v[196:199], v[226:229], v[0:15]
	ds_read_b128 v[192:195], v191 offset:32
	ds_read_b128 v[196:199], v191 offset:4640
	ds_read_b128 v[214:217], v230 offset:32
	ds_read_b128 v[218:221], v230 offset:4640
	ds_read_b128 v[222:225], v230 offset:9248
	ds_read_b128 v[226:229], v230 offset:13856
	s_waitcnt lgkmcnt(2)
	v_mfma_f32_32x32x16_bf16 v[112:127], v[192:195], v[214:217], v[112:127]
	v_mfma_f32_32x32x16_bf16 v[96:111], v[192:195], v[218:221], v[96:111]
	s_waitcnt lgkmcnt(0)
	v_mfma_f32_32x32x16_bf16 v[80:95], v[192:195], v[222:225], v[80:95]
	v_mfma_f32_32x32x16_bf16 v[64:79], v[192:195], v[226:229], v[64:79]
	v_mfma_f32_32x32x16_bf16 v[48:63], v[196:199], v[214:217], v[48:63]
	v_mfma_f32_32x32x16_bf16 v[32:47], v[196:199], v[218:221], v[32:47]
	v_mfma_f32_32x32x16_bf16 v[16:31], v[196:199], v[222:225], v[16:31]
	v_mfma_f32_32x32x16_bf16 v[0:15], v[196:199], v[226:229], v[0:15]
	ds_read_b128 v[192:195], v191 offset:64
	ds_read_b128 v[196:199], v191 offset:4672
	ds_read_b128 v[214:217], v230 offset:64
	ds_read_b128 v[218:221], v230 offset:4672
	ds_read_b128 v[222:225], v230 offset:9280
	ds_read_b128 v[226:229], v230 offset:13888
	s_waitcnt lgkmcnt(2)
	v_mfma_f32_32x32x16_bf16 v[112:127], v[192:195], v[214:217], v[112:127]
	v_mfma_f32_32x32x16_bf16 v[96:111], v[192:195], v[218:221], v[96:111]
	s_waitcnt vmcnt(7)
	ds_write_b128 v231, v[158:161]
	s_waitcnt lgkmcnt(1)
	v_mfma_f32_32x32x16_bf16 v[80:95], v[192:195], v[222:225], v[80:95]
	v_mfma_f32_32x32x16_bf16 v[64:79], v[192:195], v[226:229], v[64:79]
	s_waitcnt vmcnt(5)
	ds_write_b128 v231, v[154:157] offset:9216
	v_mfma_f32_32x32x16_bf16 v[48:63], v[196:199], v[214:217], v[48:63]
	v_mfma_f32_32x32x16_bf16 v[32:47], v[196:199], v[218:221], v[32:47]
	s_waitcnt vmcnt(4)
	ds_write_b128 v231, v[150:153] offset:18432
	v_mfma_f32_32x32x16_bf16 v[16:31], v[196:199], v[222:225], v[16:31]
	v_mfma_f32_32x32x16_bf16 v[0:15], v[196:199], v[226:229], v[0:15]
	s_waitcnt vmcnt(3)
	ds_write_b128 v231, v[146:149] offset:27648
	ds_read_b128 v[146:149], v191 offset:96
	ds_read_b128 v[150:153], v191 offset:4704
	ds_read_b128 v[154:157], v230 offset:96
	ds_read_b128 v[158:161], v230 offset:4704
	ds_read_b128 v[192:195], v230 offset:9312
	ds_read_b128 v[196:199], v230 offset:13920
	s_waitcnt lgkmcnt(2)
	v_mfma_f32_32x32x16_bf16 v[112:127], v[146:149], v[154:157], v[112:127]
	v_mfma_f32_32x32x16_bf16 v[96:111], v[146:149], v[158:161], v[96:111]
	ds_write_b128 v231, v[142:145] offset:36864
	s_waitcnt lgkmcnt(1)
	v_mfma_f32_32x32x16_bf16 v[80:95], v[146:149], v[192:195], v[80:95]
	v_mfma_f32_32x32x16_bf16 v[64:79], v[146:149], v[196:199], v[64:79]
	s_waitcnt vmcnt(2)
	ds_write_b128 v231, v[136:139] offset:46080
	v_mfma_f32_32x32x16_bf16 v[48:63], v[150:153], v[154:157], v[48:63]
	v_mfma_f32_32x32x16_bf16 v[32:47], v[150:153], v[158:161], v[32:47]
	s_waitcnt vmcnt(1)
	ds_write_b128 v231, v[132:135] offset:55296
	v_mfma_f32_32x32x16_bf16 v[16:31], v[150:153], v[192:195], v[16:31]
	v_mfma_f32_32x32x16_bf16 v[0:15], v[150:153], v[196:199], v[0:15]
	s_waitcnt vmcnt(0)
	ds_write_b128 v231, v[128:131] offset:64512
	s_add_i32 s27, s1, 0x80
	s_cmp_lt_u32 s24, 14
	s_cselect_b32 s96, s27, s1
	s_lshl_b64 s[36:37], s[96:97], 1
	v_lshl_add_u64 v[128:129], v[168:169], 0, s[36:37]
	v_lshl_add_u64 v[130:131], v[172:173], 0, s[36:37]
	global_load_dwordx4 v[158:161], v[128:129], off
	global_load_dwordx4 v[154:157], v[130:131], off
	v_lshl_add_u64 v[128:129], v[174:175], 0, s[36:37]
	v_lshl_add_u64 v[130:131], v[176:177], 0, s[36:37]
	global_load_dwordx4 v[150:153], v[128:129], off
	global_load_dwordx4 v[146:149], v[130:131], off
	v_lshl_add_u64 v[128:129], v[170:171], 0, s[36:37]
	v_lshl_add_u64 v[130:131], v[178:179], 0, s[36:37]
	global_load_dwordx4 v[142:145], v[128:129], off
	global_load_dwordx4 v[136:139], v[130:131], off
	v_lshl_add_u64 v[128:129], v[180:181], 0, s[36:37]
	v_lshl_add_u64 v[130:131], v[182:183], 0, s[36:37]
	global_load_dwordx4 v[132:135], v[128:129], off
	s_nop 0
	global_load_dwordx4 v[128:131], v[130:131], off
	s_add_i32 s1, s1, 64
	s_cmp_eq_u32 s25, 16
	s_mov_b32 s24, s25
	s_waitcnt lgkmcnt(0)
	s_barrier
; DI int crow(int i, int h) { return (i & 3) + 8 * (i >> 2) + 4 * h; }
;   DI void operator()(f32x16 (&acc)[4], int tok0, int nt, int lane, bool part = false) const {
;     const int l31 = lane & 31, hh = lane >> 5;
; #pragma unroll
;     for (int nb = 0; nb < 4; ++nb) {
;       int col = nt * 128 + nb * 32 + l31;
;       if (col < 704) {
; #pragma unroll
;         for (int i = 0; i < 16; ++i) raw[(size_t)(tok0 + crow(i, hh)) * 704 + col] = acc[nb][i];
;       }
;     }
;   }
	s_cbranch_scc0 .LBB0_910
	s_waitcnt vmcnt(0)
	v_lshl_or_b32 v130, s28, 8, v186
	v_lshl_add_u32 v131, s0, 1, v184
	v_readfirstlane_b32 s0, v130
	v_readfirstlane_b32 s1, v131
	s_nop 0
	v_add_u32_e32 v149, s0, v190
	v_lshl_or_b32 v128, s1, 7, v185
	s_movk_i32 s0, 0x2c0
	v_cmp_gt_i32_e32 vcc, s0, v128
	v_add_u32_e32 v148, 1, v149
	v_add_u32_e32 v147, 2, v149
	v_add_u32_e32 v146, 3, v149
	v_add_u32_e32 v145, 8, v149
	v_add_u32_e32 v144, 9, v149
	v_add_u32_e32 v143, 10, v149
	v_add_u32_e32 v142, 11, v149
	v_add_u32_e32 v139, 16, v149
	v_add_u32_e32 v138, 17, v149
	v_add_u32_e32 v137, 18, v149
	v_add_u32_e32 v136, 19, v149
	v_add_u32_e32 v135, 24, v149
	v_add_u32_e32 v134, 25, v149
	v_add_u32_e32 v133, 26, v149
	v_add_u32_e32 v132, 27, v149
	s_and_saveexec_b64 s[0:1], vcc
	s_cbranch_execz .LBB0_913
	v_ashrrev_i32_e32 v129, 31, v128
	v_lshl_add_u64 v[150:151], v[128:129], 2, s[52:53]
	s_movk_i32 s27, 0xb00
	v_mad_i64_i32 v[152:153], s[24:25], v149, s27, v[150:151]
	global_store_dword v[152:153], v112, off
	v_mad_i64_i32 v[152:153], s[24:25], v148, s27, v[150:151]
	global_store_dword v[152:153], v113, off
	v_mad_i64_i32 v[112:113], s[24:25], v147, s27, v[150:151]
	global_store_dword v[112:113], v114, off
	v_mad_i64_i32 v[112:113], s[24:25], v146, s27, v[150:151]
	global_store_dword v[112:113], v115, off
	v_mad_i64_i32 v[112:113], s[24:25], v145, s27, v[150:151]
	global_store_dword v[112:113], v116, off
	v_mad_i64_i32 v[112:113], s[24:25], v144, s27, v[150:151]
	global_store_dword v[112:113], v117, off
	v_mad_i64_i32 v[112:113], s[24:25], v143, s27, v[150:151]
	global_store_dword v[112:113], v118, off
	v_mad_i64_i32 v[112:113], s[24:25], v142, s27, v[150:151]
	global_store_dword v[112:113], v119, off
	v_mad_i64_i32 v[112:113], s[24:25], v139, s27, v[150:151]
	global_store_dword v[112:113], v120, off
	v_mad_i64_i32 v[112:113], s[24:25], v138, s27, v[150:151]
	global_store_dword v[112:113], v121, off
	v_mad_i64_i32 v[112:113], s[24:25], v137, s27, v[150:151]
	global_store_dword v[112:113], v122, off
	v_mad_i64_i32 v[112:113], s[24:25], v136, s27, v[150:151]
	global_store_dword v[112:113], v123, off
	v_mad_i64_i32 v[112:113], s[24:25], v135, s27, v[150:151]
	global_store_dword v[112:113], v124, off
	v_mad_i64_i32 v[112:113], s[24:25], v134, s27, v[150:151]
	global_store_dword v[112:113], v125, off
	v_mad_i64_i32 v[112:113], s[24:25], v133, s27, v[150:151]
	global_store_dword v[112:113], v126, off
	s_movk_i32 s8, 0xb00
	v_mad_i64_i32 v[112:113], s[24:25], v132, s27, v[150:151]
	global_store_dword v[112:113], v127, off
